# also relax the drain at the end of the ple GEMM to vmcnt(16) (swapped workgroups continue with the up GEMM)
# baseline (speedup 1.0000x reference)
; DI float bflo(unsigned w) { return __uint_as_float(w << 16); }
; DI float bfhi(unsigned w) { return __uint_as_float(w & 0xffff0000u); }
; DI u32x4 pack8(const f32x4& a, const f32x4& b) { u32x4 w; w.x = pack2(a[0], a[1]); w.y = pack2(a[2], a[3]); w.z = pack2(b[0], b[1]); w.w = pack2(b[2], b[3]); return w; }
; template <class F> DI void epi_rows(const pg8::f32x4 (&acc)[2][2][4][2], const pg8::Unit& u, int wr, int wc, int fr, int fq, F f) {
; #pragma unroll
;     for (int ai = 0; ai < 2; ++ai)
; #pragma unroll
;         for (int m = 0; m < 4; ++m) {
;             const int row = u.pm * 256 + ai * 128 + wr * 64 + m * 16 + fr;
; #pragma unroll
;             for (int bj = 0; bj < 2; ++bj) f(row, u.pn * 256 + bj * 128 + wc * 32 + 8 * fq, acc[ai][bj][m][0], acc[ai][bj][m][1]);
;         }
;     DI void operator()(const pg8::f32x4 (&acc)[2][2][4][2], const pg8::Unit& u, int wr, int wc, int fr, int fq) const {
;         epi_rows(acc, u, wr, wc, fr, fq, [&](int row, int col, const f32x4& a, const f32x4& b) {
;             u32x4* p = (u32x4*)(pg + (size_t)row * DM + col);
;             const u32x4 w = *p;
;             f32x4 ra, rb;
;             ra[0] = a[0] * bflo(w.x); ra[1] = a[1] * bfhi(w.x); ra[2] = a[2] * bflo(w.y); ra[3] = a[3] * bfhi(w.y);
;             rb[0] = b[0] * bflo(w.z); rb[1] = b[1] * bfhi(w.z); rb[2] = b[2] * bflo(w.w); rb[3] = b[3] * bfhi(w.w);
;             *p = pack8(ra, rb);
;         });
.LBB0_872:
	s_lshl_b32 s21, s28, 8
	v_add_u32_e32 v152, s21, v162
	v_ashrrev_i32_e32 v153, 31, v152
	v_lshl_or_b32 v130, s58, 8, v167
	v_lshlrev_b64 v[128:129], 11, v[152:153]
	v_ashrrev_i32_e32 v131, 31, v130
	v_lshl_add_u64 v[128:129], s[6:7], 0, v[128:129]
	v_lshlrev_b64 v[154:155], 1, v[130:131]
	v_lshl_add_u64 v[158:159], v[128:129], 0, v[154:155]
	v_add_u32_e32 v128, s21, v171
	v_ashrrev_i32_e32 v129, 31, v128
	v_lshlrev_b64 v[128:129], 11, v[128:129]
	v_lshl_add_u64 v[128:129], s[6:7], 0, v[128:129]
	global_load_dwordx4 v[132:135], v[158:159], off
	global_load_dwordx4 v[172:175], v[158:159], off offset:256
	v_lshl_add_u64 v[148:149], v[128:129], 0, v[154:155]
	v_add_u32_e32 v128, s21, v254
	global_load_dwordx4 v[176:179], v[148:149], off
	global_load_dwordx4 v[180:183], v[148:149], off offset:256
	v_ashrrev_i32_e32 v129, 31, v128
	v_lshlrev_b64 v[128:129], 11, v[128:129]
	v_lshl_add_u64 v[128:129], s[6:7], 0, v[128:129]
	v_lshl_add_u64 v[160:161], v[128:129], 0, v[154:155]
	global_load_dwordx4 v[184:187], v[160:161], off
	v_add_u32_e32 v128, s21, v166
	v_ashrrev_i32_e32 v129, 31, v128
	v_lshlrev_b64 v[128:129], 11, v[128:129]
	v_lshl_add_u64 v[128:129], s[6:7], 0, v[128:129]
	v_lshl_add_u64 v[156:157], v[128:129], 0, v[154:155]
	global_load_dwordx4 v[188:191], v[160:161], off offset:256
	global_load_dwordx4 v[136:139], v[156:157], off
	global_load_dwordx4 v[128:131], v[156:157], off offset:256
	s_andn2_b64 vcc, exec, s[2:3]
	s_mov_b64 s[2:3], -1
	s_waitcnt vmcnt(0)
	v_lshlrev_b32_e32 v164, 16, v132
	v_and_b32_e32 v165, 0xffff0000, v132
	v_lshlrev_b32_e32 v132, 16, v133
	v_and_b32_e32 v133, 0xffff0000, v133
	v_lshlrev_b32_e32 v192, 16, v134
	v_and_b32_e32 v193, 0xffff0000, v134
	v_lshlrev_b32_e32 v134, 16, v135
	v_and_b32_e32 v135, 0xffff0000, v135
	v_lshlrev_b32_e32 v194, 16, v172
	v_and_b32_e32 v195, 0xffff0000, v172
	v_lshlrev_b32_e32 v172, 16, v173
	v_and_b32_e32 v173, 0xffff0000, v173
	v_lshlrev_b32_e32 v196, 16, v174
	v_and_b32_e32 v197, 0xffff0000, v174
	v_lshlrev_b32_e32 v174, 16, v175
	v_and_b32_e32 v175, 0xffff0000, v175
	v_lshlrev_b32_e32 v198, 16, v176
	v_and_b32_e32 v199, 0xffff0000, v176
	v_lshlrev_b32_e32 v176, 16, v177
	v_and_b32_e32 v177, 0xffff0000, v177
	v_lshlrev_b32_e32 v200, 16, v178
	v_and_b32_e32 v201, 0xffff0000, v178
	v_lshlrev_b32_e32 v178, 16, v179
	v_and_b32_e32 v179, 0xffff0000, v179
	v_pk_mul_f32 v[108:109], v[108:109], v[164:165]
	v_pk_mul_f32 v[110:111], v[110:111], v[132:133]
	v_pk_mul_f32 v[112:113], v[112:113], v[192:193]
	v_pk_mul_f32 v[114:115], v[114:115], v[134:135]
	v_lshlrev_b32_e32 v204, 16, v182
	v_pk_mul_f32 v[120:121], v[120:121], v[194:195]
	v_pk_mul_f32 v[122:123], v[122:123], v[172:173]
	v_pk_mul_f32 v[124:125], v[124:125], v[196:197]
	v_pk_mul_f32 v[126:127], v[126:127], v[174:175]
	v_pk_mul_f32 v[132:133], v[100:101], v[198:199]
	v_pk_mul_f32 v[134:135], v[102:103], v[176:177]
	v_pk_mul_f32 v[164:165], v[104:105], v[200:201]
	v_pk_mul_f32 v[172:173], v[106:107], v[178:179]
	v_cvt_pk_bf16_f32 v100, v108, v109
	v_cvt_pk_bf16_f32 v101, v110, v111
	v_cvt_pk_bf16_f32 v102, v112, v113
	v_cvt_pk_bf16_f32 v103, v114, v115
	v_and_b32_e32 v205, 0xffff0000, v182
	v_lshlrev_b32_e32 v202, 16, v180
	v_and_b32_e32 v203, 0xffff0000, v180
	v_lshlrev_b32_e32 v180, 16, v181
	v_and_b32_e32 v181, 0xffff0000, v181
	v_cvt_pk_bf16_f32 v104, v120, v121
	v_cvt_pk_bf16_f32 v105, v122, v123
	v_cvt_pk_bf16_f32 v106, v124, v125
	v_cvt_pk_bf16_f32 v107, v126, v127
	v_cvt_pk_bf16_f32 v108, v132, v133
	v_cvt_pk_bf16_f32 v109, v134, v135
	v_cvt_pk_bf16_f32 v110, v164, v165
	v_cvt_pk_bf16_f32 v111, v172, v173
	global_store_dwordx4 v[158:159], v[100:103], off
	global_store_dwordx4 v[158:159], v[104:107], off offset:256
	global_store_dwordx4 v[148:149], v[108:111], off
	v_pk_mul_f32 v[100:101], v[96:97], v[204:205]
	v_lshlrev_b32_e32 v96, 16, v183
	v_and_b32_e32 v97, 0xffff0000, v183
	v_pk_mul_f32 v[116:117], v[116:117], v[202:203]
	v_pk_mul_f32 v[118:119], v[118:119], v[180:181]
	v_pk_mul_f32 v[102:103], v[98:99], v[96:97]
	v_cvt_pk_bf16_f32 v96, v116, v117
	v_cvt_pk_bf16_f32 v97, v118, v119
	v_cvt_pk_bf16_f32 v98, v100, v101
	v_cvt_pk_bf16_f32 v99, v102, v103
	global_store_dwordx4 v[148:149], v[96:99], off offset:256
	v_lshlrev_b32_e32 v102, 16, v185
	v_and_b32_e32 v103, 0xffff0000, v185
	v_lshlrev_b32_e32 v96, 16, v184
	v_and_b32_e32 v97, 0xffff0000, v184
	v_pk_mul_f32 v[100:101], v[92:93], v[96:97]
	v_add_u32_e32 v92, 0x80, v152
	v_ashrrev_i32_e32 v93, 31, v92
	v_lshlrev_b64 v[92:93], 11, v[92:93]
	v_lshl_add_u64 v[92:93], s[6:7], 0, v[92:93]
	v_lshl_add_u64 v[92:93], v[92:93], 0, v[154:155]
	global_load_dwordx4 v[96:99], v[92:93], off
	v_pk_mul_f32 v[94:95], v[94:95], v[102:103]
	v_lshlrev_b32_e32 v102, 16, v186
	v_and_b32_e32 v103, 0xffff0000, v186
	v_pk_mul_f32 v[102:103], v[88:89], v[102:103]
	v_lshlrev_b32_e32 v88, 16, v187
	v_and_b32_e32 v89, 0xffff0000, v187
	v_pk_mul_f32 v[104:105], v[90:91], v[88:89]
	v_cvt_pk_bf16_f32 v88, v100, v101
	v_cvt_pk_bf16_f32 v89, v94, v95
	v_cvt_pk_bf16_f32 v90, v102, v103
	v_cvt_pk_bf16_f32 v91, v104, v105
	global_store_dwordx4 v[160:161], v[88:91], off
	v_lshlrev_b32_e32 v94, 16, v189
	v_and_b32_e32 v95, 0xffff0000, v189
	v_lshlrev_b32_e32 v88, 16, v188
	v_and_b32_e32 v89, 0xffff0000, v188
	v_pk_mul_f32 v[84:85], v[84:85], v[88:89]
	global_load_dwordx4 v[88:91], v[92:93], off offset:256
	v_pk_mul_f32 v[86:87], v[86:87], v[94:95]
	v_lshlrev_b32_e32 v94, 16, v190
	v_and_b32_e32 v95, 0xffff0000, v190
	v_pk_mul_f32 v[94:95], v[80:81], v[94:95]
	v_lshlrev_b32_e32 v80, 16, v191
	v_and_b32_e32 v81, 0xffff0000, v191
	v_pk_mul_f32 v[100:101], v[82:83], v[80:81]
	v_cvt_pk_bf16_f32 v80, v84, v85
; DI float bflo(unsigned w) { return __uint_as_float(w << 16); }
; DI float bfhi(unsigned w) { return __uint_as_float(w & 0xffff0000u); }
; DI u32x4 pack8(const f32x4& a, const f32x4& b) { u32x4 w; w.x = pack2(a[0], a[1]); w.y = pack2(a[2], a[3]); w.z = pack2(b[0], b[1]); w.w = pack2(b[2], b[3]); return w; }
;     DI void operator()(const pg8::f32x4 (&acc)[2][2][4][2], const pg8::Unit& u, int wr, int wc, int fr, int fq) const {
;         epi_rows(acc, u, wr, wc, fr, fq, [&](int row, int col, const f32x4& a, const f32x4& b) {
;             u32x4* p = (u32x4*)(pg + (size_t)row * DM + col);
;             const u32x4 w = *p;
;             f32x4 ra, rb;
;             ra[0] = a[0] * bflo(w.x); ra[1] = a[1] * bfhi(w.x); ra[2] = a[2] * bflo(w.y); ra[3] = a[3] * bfhi(w.y);
;             rb[0] = b[0] * bflo(w.z); rb[1] = b[1] * bfhi(w.z); rb[2] = b[2] * bflo(w.w); rb[3] = b[3] * bfhi(w.w);
;             *p = pack8(ra, rb);
;         });
	v_cvt_pk_bf16_f32 v81, v86, v87
	v_cvt_pk_bf16_f32 v82, v94, v95
	v_cvt_pk_bf16_f32 v83, v100, v101
	global_store_dwordx4 v[160:161], v[80:83], off offset:256
	v_lshlrev_b32_e32 v86, 16, v137
	v_and_b32_e32 v87, 0xffff0000, v137
	v_lshlrev_b32_e32 v80, 16, v136
	v_and_b32_e32 v81, 0xffff0000, v136
	v_pk_mul_f32 v[84:85], v[76:77], v[80:81]
	v_add_u32_e32 v76, 0x90, v152
	v_ashrrev_i32_e32 v77, 31, v76
	v_lshlrev_b64 v[76:77], 11, v[76:77]
	v_lshl_add_u64 v[76:77], s[6:7], 0, v[76:77]
	v_lshl_add_u64 v[76:77], v[76:77], 0, v[154:155]
	global_load_dwordx4 v[80:83], v[76:77], off
	v_pk_mul_f32 v[78:79], v[78:79], v[86:87]
	v_lshlrev_b32_e32 v86, 16, v138
	v_and_b32_e32 v87, 0xffff0000, v138
	v_pk_mul_f32 v[86:87], v[72:73], v[86:87]
	v_lshlrev_b32_e32 v72, 16, v139
	v_and_b32_e32 v73, 0xffff0000, v139
	v_pk_mul_f32 v[94:95], v[74:75], v[72:73]
	v_cvt_pk_bf16_f32 v73, v78, v79
	v_lshlrev_b32_e32 v78, 16, v129
	v_and_b32_e32 v79, 0xffff0000, v129
	v_pk_mul_f32 v[70:71], v[70:71], v[78:79]
	v_lshlrev_b32_e32 v78, 16, v130
	v_and_b32_e32 v79, 0xffff0000, v130
	v_pk_mul_f32 v[78:79], v[64:65], v[78:79]
	v_lshlrev_b32_e32 v64, 16, v131
	v_and_b32_e32 v65, 0xffff0000, v131
	v_cvt_pk_bf16_f32 v72, v84, v85
	v_pk_mul_f32 v[84:85], v[66:67], v[64:65]
	v_add_u32_e32 v66, 0xa0, v152
	v_cvt_pk_bf16_f32 v74, v86, v87
	v_cvt_pk_bf16_f32 v75, v94, v95
	v_ashrrev_i32_e32 v67, 31, v66
	global_store_dwordx4 v[156:157], v[72:75], off
	v_lshlrev_b64 v[66:67], 11, v[66:67]
	v_lshl_add_u64 v[66:67], s[6:7], 0, v[66:67]
	v_lshlrev_b32_e32 v72, 16, v128
	v_and_b32_e32 v73, 0xffff0000, v128
	v_pk_mul_f32 v[68:69], v[68:69], v[72:73]
	global_load_dwordx4 v[72:75], v[76:77], off offset:256
	v_cvt_pk_bf16_f32 v64, v68, v69
	v_cvt_pk_bf16_f32 v65, v70, v71
	v_lshl_add_u64 v[86:87], v[66:67], 0, v[154:155]
	v_cvt_pk_bf16_f32 v66, v78, v79
	v_cvt_pk_bf16_f32 v67, v84, v85
	global_store_dwordx4 v[156:157], v[64:67], off offset:256
	global_load_dwordx4 v[68:71], v[86:87], off
	s_waitcnt vmcnt(8)
	v_lshlrev_b32_e32 v64, 16, v96
	v_and_b32_e32 v65, 0xffff0000, v96
	v_pk_mul_f32 v[60:61], v[60:61], v[64:65]
	v_lshlrev_b32_e32 v64, 16, v97
	v_and_b32_e32 v65, 0xffff0000, v97
	v_pk_mul_f32 v[64:65], v[62:63], v[64:65]
	v_lshlrev_b32_e32 v62, 16, v98
	v_and_b32_e32 v63, 0xffff0000, v98
	v_pk_mul_f32 v[66:67], v[56:57], v[62:63]
	v_lshlrev_b32_e32 v56, 16, v99
	v_and_b32_e32 v57, 0xffff0000, v99
	v_pk_mul_f32 v[78:79], v[58:59], v[56:57]
	v_cvt_pk_bf16_f32 v56, v60, v61
	v_cvt_pk_bf16_f32 v57, v64, v65
	v_cvt_pk_bf16_f32 v58, v66, v67
	v_cvt_pk_bf16_f32 v59, v78, v79
	global_store_dwordx4 v[92:93], v[56:59], off
	global_load_dwordx4 v[60:63], v[86:87], off offset:256
	s_waitcnt vmcnt(8)
	v_lshlrev_b32_e32 v64, 16, v90
	v_lshlrev_b32_e32 v56, 16, v88
	v_and_b32_e32 v57, 0xffff0000, v88
	v_pk_mul_f32 v[56:57], v[52:53], v[56:57]
	v_lshlrev_b32_e32 v52, 16, v89
	v_and_b32_e32 v53, 0xffff0000, v89
	v_pk_mul_f32 v[58:59], v[54:55], v[52:53]
	v_add_u32_e32 v52, 0xb0, v152
	v_ashrrev_i32_e32 v53, 31, v52
	v_lshlrev_b64 v[52:53], 11, v[52:53]
	v_lshl_add_u64 v[52:53], s[6:7], 0, v[52:53]
	v_lshl_add_u64 v[66:67], v[52:53], 0, v[154:155]
	global_load_dwordx4 v[52:55], v[66:67], off
	v_and_b32_e32 v65, 0xffff0000, v90
	v_pk_mul_f32 v[64:65], v[48:49], v[64:65]
	v_lshlrev_b32_e32 v48, 16, v91
	v_and_b32_e32 v49, 0xffff0000, v91
	v_pk_mul_f32 v[78:79], v[50:51], v[48:49]
	v_cvt_pk_bf16_f32 v48, v56, v57
	v_cvt_pk_bf16_f32 v49, v58, v59
	v_cvt_pk_bf16_f32 v50, v64, v65
	v_cvt_pk_bf16_f32 v51, v78, v79
	global_store_dwordx4 v[92:93], v[48:51], off offset:256
	s_waitcnt vmcnt(8)
; DI float bflo(unsigned w) { return __uint_as_float(w << 16); }
; DI float bfhi(unsigned w) { return __uint_as_float(w & 0xffff0000u); }
; #define PG8_WAIT_V(n) asm volatile("s_waitcnt vmcnt(" #n ")" ::: "memory")
; #define PG8_BAR __builtin_amdgcn_s_barrier()
; DI u32x4 pack8(const f32x4& a, const f32x4& b) { u32x4 w; w.x = pack2(a[0], a[1]); w.y = pack2(a[2], a[3]); w.z = pack2(b[0], b[1]); w.w = pack2(b[2], b[3]); return w; }
; template <class Epi, class Sched, bool ALIGN_EPI = false, bool SP2 = false>
; __device__ __forceinline__ void gemm_phase(PG8_LAS unsigned char* lds, const Gemm g, const Sched& S, const Epi& E, const int wid_s) {
;     ...
;     PG8_WAIT_V(0);
;     if constexpr (!ALIGN_EPI) { if (wr == 0) PG8_BAR; }
;     PG8_BAR;
;     DI void operator()(const pg8::f32x4 (&acc)[2][2][4][2], const pg8::Unit& u, int wr, int wc, int fr, int fq) const {
;         epi_rows(acc, u, wr, wc, fr, fq, [&](int row, int col, const f32x4& a, const f32x4& b) {
;             u32x4* p = (u32x4*)(pg + (size_t)row * DM + col);
;             const u32x4 w = *p;
;             f32x4 ra, rb;
;             ra[0] = a[0] * bflo(w.x); ra[1] = a[1] * bfhi(w.x); ra[2] = a[2] * bflo(w.y); ra[3] = a[3] * bfhi(w.y);
;             rb[0] = b[0] * bflo(w.z); rb[1] = b[1] * bfhi(w.z); rb[2] = b[2] * bflo(w.w); rb[3] = b[3] * bfhi(w.w);
;             *p = pack8(ra, rb);
;         });
	v_lshlrev_b32_e32 v56, 16, v82
	v_and_b32_e32 v57, 0xffff0000, v82
	v_lshlrev_b32_e32 v48, 16, v80
	v_and_b32_e32 v49, 0xffff0000, v80
	v_pk_mul_f32 v[48:49], v[44:45], v[48:49]
	v_lshlrev_b32_e32 v44, 16, v81
	v_and_b32_e32 v45, 0xffff0000, v81
	v_pk_mul_f32 v[50:51], v[46:47], v[44:45]
	global_load_dwordx4 v[44:47], v[66:67], off offset:256
	v_pk_mul_f32 v[56:57], v[32:33], v[56:57]
	v_lshlrev_b32_e32 v32, 16, v83
	v_and_b32_e32 v33, 0xffff0000, v83
	v_pk_mul_f32 v[58:59], v[34:35], v[32:33]
	v_cvt_pk_bf16_f32 v32, v48, v49
	v_cvt_pk_bf16_f32 v33, v50, v51
	v_cvt_pk_bf16_f32 v34, v56, v57
	v_cvt_pk_bf16_f32 v35, v58, v59
	global_store_dwordx4 v[76:77], v[32:35], off
	s_waitcnt vmcnt(8)
	s_nop 0
	v_lshlrev_b32_e32 v32, 16, v72
	v_and_b32_e32 v33, 0xffff0000, v72
	v_pk_mul_f32 v[32:33], v[40:41], v[32:33]
	v_lshlrev_b32_e32 v40, 16, v74
	v_and_b32_e32 v41, 0xffff0000, v74
	v_lshlrev_b32_e32 v34, 16, v73
	v_and_b32_e32 v35, 0xffff0000, v73
	v_pk_mul_f32 v[36:37], v[36:37], v[40:41]
	v_lshlrev_b32_e32 v40, 16, v75
	v_and_b32_e32 v41, 0xffff0000, v75
	v_pk_mul_f32 v[34:35], v[42:43], v[34:35]
	v_pk_mul_f32 v[38:39], v[38:39], v[40:41]
	v_cvt_pk_bf16_f32 v32, v32, v33
	v_cvt_pk_bf16_f32 v33, v34, v35
	v_cvt_pk_bf16_f32 v34, v36, v37
	v_cvt_pk_bf16_f32 v35, v38, v39
	global_store_dwordx4 v[76:77], v[32:35], off offset:256
	s_waitcnt vmcnt(7)
	s_nop 0
	v_lshlrev_b32_e32 v32, 16, v68
	v_and_b32_e32 v33, 0xffff0000, v68
	v_pk_mul_f32 v[24:25], v[24:25], v[32:33]
	v_lshlrev_b32_e32 v32, 16, v69
	v_and_b32_e32 v33, 0xffff0000, v69
	v_pk_mul_f32 v[26:27], v[26:27], v[32:33]
	v_lshlrev_b32_e32 v32, 16, v70
	v_and_b32_e32 v33, 0xffff0000, v70
	v_pk_mul_f32 v[32:33], v[16:17], v[32:33]
	v_lshlrev_b32_e32 v16, 16, v71
	v_and_b32_e32 v17, 0xffff0000, v71
	v_pk_mul_f32 v[34:35], v[18:19], v[16:17]
	v_cvt_pk_bf16_f32 v16, v24, v25
	v_cvt_pk_bf16_f32 v17, v26, v27
	v_cvt_pk_bf16_f32 v18, v32, v33
	v_cvt_pk_bf16_f32 v19, v34, v35
	s_waitcnt vmcnt(5)
	v_lshlrev_b32_e32 v24, 16, v62
	v_and_b32_e32 v25, 0xffff0000, v62
	global_store_dwordx4 v[86:87], v[16:19], off
	v_pk_mul_f32 v[20:21], v[20:21], v[24:25]
	v_lshlrev_b32_e32 v24, 16, v63
	v_lshlrev_b32_e32 v16, 16, v60
	v_and_b32_e32 v17, 0xffff0000, v60
	v_lshlrev_b32_e32 v18, 16, v61
	v_and_b32_e32 v19, 0xffff0000, v61
	v_and_b32_e32 v25, 0xffff0000, v63
	v_pk_mul_f32 v[16:17], v[28:29], v[16:17]
	v_pk_mul_f32 v[18:19], v[30:31], v[18:19]
	v_pk_mul_f32 v[22:23], v[22:23], v[24:25]
	v_cvt_pk_bf16_f32 v16, v16, v17
	v_cvt_pk_bf16_f32 v17, v18, v19
	v_cvt_pk_bf16_f32 v18, v20, v21
	v_cvt_pk_bf16_f32 v19, v22, v23
	global_store_dwordx4 v[86:87], v[16:19], off offset:256
	s_waitcnt vmcnt(6)
	s_nop 0
	v_lshlrev_b32_e32 v16, 16, v52
	v_and_b32_e32 v17, 0xffff0000, v52
	v_pk_mul_f32 v[12:13], v[12:13], v[16:17]
	v_lshlrev_b32_e32 v16, 16, v53
	v_and_b32_e32 v17, 0xffff0000, v53
	v_pk_mul_f32 v[14:15], v[14:15], v[16:17]
	v_lshlrev_b32_e32 v16, 16, v54
	v_and_b32_e32 v17, 0xffff0000, v54
	v_pk_mul_f32 v[16:17], v[8:9], v[16:17]
	v_lshlrev_b32_e32 v8, 16, v55
	v_and_b32_e32 v9, 0xffff0000, v55
	v_pk_mul_f32 v[18:19], v[10:11], v[8:9]
	v_cvt_pk_bf16_f32 v8, v12, v13
	v_cvt_pk_bf16_f32 v9, v14, v15
	v_cvt_pk_bf16_f32 v10, v16, v17
	v_cvt_pk_bf16_f32 v11, v18, v19
	global_store_dwordx4 v[66:67], v[8:11], off
	s_waitcnt vmcnt(5)
	s_nop 0
	v_lshlrev_b32_e32 v8, 16, v44
	v_and_b32_e32 v9, 0xffff0000, v44
	v_pk_mul_f32 v[4:5], v[4:5], v[8:9]
	v_lshlrev_b32_e32 v8, 16, v45
	v_and_b32_e32 v9, 0xffff0000, v45
	v_pk_mul_f32 v[6:7], v[6:7], v[8:9]
	v_lshlrev_b32_e32 v8, 16, v46
	v_and_b32_e32 v9, 0xffff0000, v46
	v_pk_mul_f32 v[8:9], v[0:1], v[8:9]
	v_lshlrev_b32_e32 v0, 16, v47
	v_and_b32_e32 v1, 0xffff0000, v47
	v_pk_mul_f32 v[10:11], v[2:3], v[0:1]
	v_cvt_pk_bf16_f32 v0, v4, v5
	v_cvt_pk_bf16_f32 v1, v6, v7
	v_cvt_pk_bf16_f32 v2, v8, v9
	v_cvt_pk_bf16_f32 v3, v10, v11
	global_store_dwordx4 v[66:67], v[0:3], off offset:256
	s_cbranch_vccnz .LBB0_863
	s_andn2_b64 vcc, exec, s[8:9]
	s_cbranch_vccnz .LBB0_862
	s_barrier
	s_branch .LBB0_862
.LBB0_875:
	s_waitcnt vmcnt(16)
	s_barrier
.LBB0_876:
	s_cmp_eq_u32 s98, 1
	s_cbranch_scc0 .Lp6_b7_go
	s_mov_b32 s98, 2
	s_branch .Lp6_up_entry
